# MoBA sub-tile: QK MFMA reads exponent offset from persistent per-block VGPR tuple instead of 16 v_mov per sub-tile
# speedup vs baseline: 1.0106x; 1.0106x over previous
; #define LAS __attribute__((address_space(3)))
; DI f32x16 mfma32(bf16x8 a, bf16x8 b, f32x16 c) { return __builtin_amdgcn_mfma_f32_32x32x16_bf16(a, b, c, 0, 0, 0); }
; template <int MODE>
; DI void sub_tile(const bf16x8 (&kf)[4], const bf16x8 (&vf)[2][2], const bf16x8 (&qf)[4], f32x16& o0, f32x16& o1, float& l, bool diag, float offs, float fm, const LAS float* fsp, int r, int h) {
;     ...
;     if (MODE == 2) {
; #pragma unroll
;         for (int i = 0; i < 16; ++i) x[i] = offs;
; #pragma unroll
;         for (int sp = 0; sp < 4; ++sp) x = mfma32(kf[sp], qf[sp], x);
; template <int MODE>
; DI void attn_wg2_item(const bf16_t* Qm, const bf16_t* Km, const bf16_t* Vtm, const float* Fb, const float* KMPb, const bf16_t* G, bf16_t* Y, int bh, int qb2, int halfq, int mixer, float Mb, LAS unsigned char* lds, int tid, int wave, int lane) {
;     ...
;             const int tau = cur * 2 + kk, nb = tau >> 3;
;             bool actA = tau <= qtA, actB = tau <= qtB;
;             if (MODE == 2) { actA = actA && ((visA >> nb) & 1u); actB = actB && ((visB >> nb) & 1u); }
;             if (actA || actB) {
;                 bf16x8 kf[4], vf[2][2];
; #pragma unroll
;                 for (int sp = 0; sp < 4; ++sp) kf[sp] = *(LAS bf16x8*)(lb + kra + kk * 32 * 144 + sp * 32);
; #pragma unroll
;                 for (int dd = 0; dd < 2; ++dd)
; #pragma unroll
;                     for (int s = 0; s < 2; ++s) vf[dd][s] = *(LAS bf16x8*)(lb + vra + dd * 32 * 144 + kk * 64 + s * 32);
;                 float offA = mb2, offB = mb2;
;                 if (MODE == 2) { offA = ((nb == qblkA) || ((selA >> nb) & 1u)) ? mb2 : NEGI; offB = ((nb == qblkB) || ((selB >> nb) & 1u)) ? mb2 : NEGI; }
.LBB0_390:
	s_and_b32 s47, s46, 3
	s_cmp_lg_u32 s47, 3
	s_cbranch_scc1 .Lmoba_keep_offs
	s_lshr_b32 s47, s46, 2
	s_lshl_b32 s48, 1, s47
	s_cmp_eq_u32 s47, s86
	s_cselect_b64 s[92:93], -1, 0
	v_and_b32_e32 v208, s48, v163
	v_and_b32_e32 v224, s48, v171
	v_cmp_ne_u32_e32 vcc, 0, v208
	s_or_b64 vcc, vcc, s[92:93]
	s_cmp_eq_u32 s47, s78
	s_cselect_b64 s[92:93], -1, 0
	v_cndmask_b32_e32 v208, v195, v184, vcc
	v_cmp_ne_u32_e32 vcc, 0, v224
	s_or_b64 vcc, vcc, s[92:93]
	v_mov_b32_e32 v209, v208
	v_mov_b32_e32 v210, v208
	v_mov_b32_e32 v211, v208
	v_mov_b32_e32 v212, v208
	v_mov_b32_e32 v213, v208
	v_mov_b32_e32 v214, v208
	v_mov_b32_e32 v215, v208
	v_mov_b32_e32 v216, v208
	v_mov_b32_e32 v217, v208
	v_mov_b32_e32 v218, v208
	v_mov_b32_e32 v219, v208
	v_mov_b32_e32 v220, v208
	v_mov_b32_e32 v221, v208
	v_mov_b32_e32 v222, v208
	v_mov_b32_e32 v223, v208
	v_cndmask_b32_e32 v224, v195, v184, vcc
	v_mov_b32_e32 v225, v224
	v_mov_b32_e32 v226, v224
	v_mov_b32_e32 v227, v224
	v_mov_b32_e32 v228, v224
	v_mov_b32_e32 v229, v224
	v_mov_b32_e32 v230, v224
	v_mov_b32_e32 v231, v224
	v_mov_b32_e32 v232, v224
	v_mov_b32_e32 v233, v224
	v_mov_b32_e32 v234, v224
	v_mov_b32_e32 v235, v224
	v_mov_b32_e32 v236, v224
	v_mov_b32_e32 v237, v224
	v_mov_b32_e32 v238, v224
	v_mov_b32_e32 v239, v224

; #define LAS __attribute__((address_space(3)))
; DI f32x16 mfma32(bf16x8 a, bf16x8 b, f32x16 c) { return __builtin_amdgcn_mfma_f32_32x32x16_bf16(a, b, c, 0, 0, 0); }
; DI float ex2(float x) { return __builtin_amdgcn_exp2f(x); }
; template <int MODE>
; DI void sub_tile(const bf16x8 (&kf)[4], const bf16x8 (&vf)[2][2], const bf16x8 (&qf)[4], f32x16& o0, f32x16& o1, float& l, bool diag, float offs, float fm, const LAS float* fsp, int r, int h) {
;     ...
;     if (MODE == 2) {
; #pragma unroll
;         for (int i = 0; i < 16; ++i) x[i] = offs;
; #pragma unroll
;         for (int sp = 0; sp < 4; ++sp) x = mfma32(kf[sp], qf[sp], x);
; #pragma unroll
;         for (int i = 0; i < 16; ++i) p[i] = ex2(x[i]);
;     } else {
;         x = qk_tile(kf, qf);
; #pragma unroll
;         for (int g = 0; g < 4; ++g) {
;             const f32x4 fs = *(const LAS f32x4*)(fsp + 16 * (g >> 1) + 8 * h + 4 * (g & 1));
; #pragma unroll
;             for (int e = 0; e < 4; ++e) p[4 * g + e] = ex2(x[4 * g + e] + (fm - fs[e]));
;         }
;     }
;     if (diag) {
; #pragma unroll
;         for (int i = 0; i < 16; ++i) if (kidx(i, h) > r) p[i] = 0.f;
;     }
; template <int MODE>
; DI void attn_wg2_item(const bf16_t* Qm, const bf16_t* Km, const bf16_t* Vtm, const float* Fb, const float* KMPb, const bf16_t* G, bf16_t* Y, int bh, int qb2, int halfq, int mixer, float Mb, LAS unsigned char* lds, int tid, int wave, int lane) {
;     ...
;             if (actA || actB) {
;                 bf16x8 kf[4], vf[2][2];
; #pragma unroll
;                 for (int sp = 0; sp < 4; ++sp) kf[sp] = *(LAS bf16x8*)(lb + kra + kk * 32 * 144 + sp * 32);
; #pragma unroll
;                 for (int dd = 0; dd < 2; ++dd)
; #pragma unroll
;                     for (int s = 0; s < 2; ++s) vf[dd][s] = *(LAS bf16x8*)(lb + vra + dd * 32 * 144 + kk * 64 + s * 32);
;                 float offA = mb2, offB = mb2;
;                 if (MODE == 2) { offA = ((nb == qblkA) || ((selA >> nb) & 1u)) ? mb2 : NEGI; offB = ((nb == qblkB) || ((selB >> nb) & 1u)) ? mb2 : NEGI; }
;                 const LAS float* fsp = (const LAS float*)(lb + AW_F) + kk * 32;
;                 if (actA) sub_tile<MODE>(kf, vf, qfA, oA0, oA1, lA, tau == qtA, offA, fmA, fsp, r, h);
.LBB0_393:
	s_mul_i32 s47, s79, 0x4900
	s_add_i32 s47, s47, 0
	s_lshl_b32 s87, s46, 1
	s_lshr_b32 s88, s46, 2
	s_cmp_lt_i32 s87, s84
	v_add_u32_e32 v0, s47, v175
	v_add_u32_e32 v10, s47, v173
	s_cselect_b64 s[46:47], -1, 0
	s_cmp_lt_i32 s87, s85
	s_cselect_b64 s[64:65], -1, 0
	s_lshl_b32 s89, 1, s88
	v_and_b32_e32 v11, s89, v176
	v_cmp_ne_u32_e32 vcc, 0, v11
	v_and_b32_e32 v11, s89, v177
	s_and_b64 s[48:49], s[46:47], vcc
	v_cmp_ne_u32_e64 s[46:47], 0, v11
	s_and_b64 s[66:67], s[64:65], s[46:47]
	s_or_b64 s[68:69], s[48:49], s[66:67]
	v_add_u32_e32 v14, v0, v172
	v_add_u32_e32 v0, v10, v172
	s_and_saveexec_b64 s[64:65], s[68:69]
	s_cbranch_execz .LBB0_403
	ds_read_b128 v[152:155], v14 offset:4608
	ds_read_b128 v[148:151], v14 offset:4640
	ds_read_b128 v[144:147], v14 offset:4672
	ds_read_b128 v[140:143], v14 offset:4704
	ds_read_b128 v[136:139], v0 offset:9280
	ds_read_b128 v[132:135], v0 offset:9312
	ds_read_b128 v[128:131], v0 offset:13888
	ds_read_b128 v[10:13], v0 offset:13920
	s_or_b32 s90, s87, 1
	s_and_saveexec_b64 s[68:69], s[48:49]
	s_cbranch_execz .LBB0_398
	s_cmp_lg_u32 s90, s84
	s_waitcnt lgkmcnt(7)
	v_mfma_f32_32x32x16_bf16 v[80:95], v[152:155], v[96:99], v[208:223]
	s_waitcnt lgkmcnt(6)
	v_mfma_f32_32x32x16_bf16 v[80:95], v[148:151], v[100:103], v[80:95]
	s_waitcnt lgkmcnt(5)
	v_mfma_f32_32x32x16_bf16 v[80:95], v[144:147], v[104:107], v[80:95]
	s_waitcnt lgkmcnt(4)
	v_mfma_f32_32x32x16_bf16 v[80:95], v[140:143], v[108:111], v[80:95]
	s_nop 11
	v_exp_f32_e32 v15, v80
	v_exp_f32_e32 v80, v81
	v_exp_f32_e32 v81, v82
	v_exp_f32_e32 v82, v83
	v_exp_f32_e32 v188, v84
	v_exp_f32_e32 v85, v85
	v_exp_f32_e32 v190, v86
	v_exp_f32_e32 v192, v87
	v_exp_f32_e32 v83, v88
	v_exp_f32_e32 v84, v89
	v_exp_f32_e32 v86, v90
	v_exp_f32_e32 v87, v91
	v_exp_f32_e32 v88, v92
	v_exp_f32_e32 v89, v93
	v_exp_f32_e32 v90, v94
	v_exp_f32_e32 v91, v95
	s_cbranch_scc1 .LBB0_397
	v_cndmask_b32_e64 v92, v15, 0, s[12:13]
	v_cndmask_b32_e64 v15, v92, v15, s[14:15]
	v_cndmask_b32_e64 v92, v83, 0, s[28:29]
	v_cndmask_b32_e64 v80, 0, v80, s[14:15]
	v_cndmask_b32_e64 v81, v81, 0, s[16:17]
	v_cndmask_b32_e64 v82, v82, 0, s[18:19]
	v_cndmask_b32_e64 v188, v188, 0, s[20:21]
	v_cndmask_b32_e64 v85, v85, 0, s[22:23]
	v_cndmask_b32_e64 v190, v190, 0, s[24:25]
	v_cndmask_b32_e64 v192, v192, 0, s[26:27]
	v_cndmask_b32_e64 v83, v92, v83, s[30:31]
	v_cndmask_b32_e64 v84, 0, v84, s[30:31]
	v_cndmask_b32_e64 v86, v86, 0, s[34:35]
	v_cndmask_b32_e64 v87, v87, 0, s[36:37]
	v_cndmask_b32_e64 v88, v88, 0, s[38:39]
	v_cndmask_b32_e64 v89, v89, 0, s[40:41]
	v_cndmask_b32_e64 v90, v90, 0, s[42:43]
	v_cndmask_b32_e64 v91, v91, 0, s[44:45]

; #define LAS __attribute__((address_space(3)))
; DI f32x16 mfma32(bf16x8 a, bf16x8 b, f32x16 c) { return __builtin_amdgcn_mfma_f32_32x32x16_bf16(a, b, c, 0, 0, 0); }
; DI float ex2(float x) { return __builtin_amdgcn_exp2f(x); }
; template <int MODE>
; DI void sub_tile(const bf16x8 (&kf)[4], const bf16x8 (&vf)[2][2], const bf16x8 (&qf)[4], f32x16& o0, f32x16& o1, float& l, bool diag, float offs, float fm, const LAS float* fsp, int r, int h) {
;     ...
;     if (MODE == 2) {
; #pragma unroll
;         for (int i = 0; i < 16; ++i) x[i] = offs;
; #pragma unroll
;         for (int sp = 0; sp < 4; ++sp) x = mfma32(kf[sp], qf[sp], x);
; #pragma unroll
;         for (int i = 0; i < 16; ++i) p[i] = ex2(x[i]);
;     } else {
;         x = qk_tile(kf, qf);
; #pragma unroll
;         for (int g = 0; g < 4; ++g) {
;             const f32x4 fs = *(const LAS f32x4*)(fsp + 16 * (g >> 1) + 8 * h + 4 * (g & 1));
; #pragma unroll
;             for (int e = 0; e < 4; ++e) p[4 * g + e] = ex2(x[4 * g + e] + (fm - fs[e]));
;         }
;     }
;     if (diag) {
; #pragma unroll
;         for (int i = 0; i < 16; ++i) if (kidx(i, h) > r) p[i] = 0.f;
;     }
; template <int MODE>
; DI void attn_wg2_item(const bf16_t* Qm, const bf16_t* Km, const bf16_t* Vtm, const float* Fb, const float* KMPb, const bf16_t* G, bf16_t* Y, int bh, int qb2, int halfq, int mixer, float Mb, LAS unsigned char* lds, int tid, int wave, int lane) {
;     ...
;                 if (MODE == 2) { offA = ((nb == qblkA) || ((selA >> nb) & 1u)) ? mb2 : NEGI; offB = ((nb == qblkB) || ((selB >> nb) & 1u)) ? mb2 : NEGI; }
;                 const LAS float* fsp = (const LAS float*)(lb + AW_F) + kk * 32;
;                 if (actA) sub_tile<MODE>(kf, vf, qfA, oA0, oA1, lA, tau == qtA, offA, fmA, fsp, r, h);
;                 if (actB) sub_tile<MODE>(kf, vf, qfB, oB0, oB1, lB, tau == qtB, offB, fmB, fsp, r, h);
.LBB0_398:
	s_or_b64 exec, exec, s[68:69]
	s_and_saveexec_b64 s[68:69], s[66:67]
	s_cbranch_execz .LBB0_402
	s_cmp_lg_u32 s90, s85
	s_waitcnt lgkmcnt(7)
	v_mfma_f32_32x32x16_bf16 v[80:95], v[152:155], v[112:115], v[224:239]
	s_waitcnt lgkmcnt(6)
	v_mfma_f32_32x32x16_bf16 v[80:95], v[148:151], v[116:119], v[80:95]
	s_waitcnt lgkmcnt(5)
	v_mfma_f32_32x32x16_bf16 v[80:95], v[144:147], v[120:123], v[80:95]
	s_waitcnt lgkmcnt(4)
	v_mfma_f32_32x32x16_bf16 v[80:95], v[140:143], v[124:127], v[80:95]
	s_nop 11
	v_exp_f32_e32 v144, v80
	v_exp_f32_e32 v145, v81
	v_exp_f32_e32 v140, v82
	v_exp_f32_e32 v141, v83
	v_exp_f32_e32 v142, v84
	v_exp_f32_e32 v143, v85
	v_exp_f32_e32 v86, v86
	v_exp_f32_e32 v87, v87
	v_exp_f32_e32 v88, v88
	v_exp_f32_e32 v15, v89
	v_exp_f32_e32 v80, v90
	v_exp_f32_e32 v81, v91
	v_exp_f32_e32 v82, v92
	v_exp_f32_e32 v83, v93
	v_exp_f32_e32 v84, v94
	v_exp_f32_e32 v85, v95
	s_cbranch_scc1 .LBB0_401
	v_cndmask_b32_e64 v89, v144, 0, s[12:13]
	v_cndmask_b32_e64 v144, v89, v144, s[14:15]
	v_cndmask_b32_e64 v89, v88, 0, s[28:29]
	v_cndmask_b32_e64 v145, 0, v145, s[14:15]
	v_cndmask_b32_e64 v140, v140, 0, s[16:17]
	v_cndmask_b32_e64 v141, v141, 0, s[18:19]
	v_cndmask_b32_e64 v142, v142, 0, s[20:21]
	v_cndmask_b32_e64 v143, v143, 0, s[22:23]
	v_cndmask_b32_e64 v86, v86, 0, s[24:25]
	v_cndmask_b32_e64 v87, v87, 0, s[26:27]
	v_cndmask_b32_e64 v88, v89, v88, s[30:31]
	v_cndmask_b32_e64 v15, 0, v15, s[30:31]
	v_cndmask_b32_e64 v80, v80, 0, s[34:35]
	v_cndmask_b32_e64 v81, v81, 0, s[36:37]
	v_cndmask_b32_e64 v82, v82, 0, s[38:39]
	v_cndmask_b32_e64 v83, v83, 0, s[40:41]
	v_cndmask_b32_e64 v84, v84, 0, s[42:43]
	v_cndmask_b32_e64 v85, v85, 0, s[44:45]

; #define LAS __attribute__((address_space(3)))
; DI f32x16 mfma32(bf16x8 a, bf16x8 b, f32x16 c) { return __builtin_amdgcn_mfma_f32_32x32x16_bf16(a, b, c, 0, 0, 0); }
; DI float ex2(float x) { return __builtin_amdgcn_exp2f(x); }
; template <int MODE>
; DI void sub_tile(const bf16x8 (&kf)[4], const bf16x8 (&vf)[2][2], const bf16x8 (&qf)[4], f32x16& o0, f32x16& o1, float& l, bool diag, float offs, float fm, const LAS float* fsp, int r, int h) {
;     ...
;     if (MODE == 2) {
; #pragma unroll
;         for (int i = 0; i < 16; ++i) x[i] = offs;
; #pragma unroll
;         for (int sp = 0; sp < 4; ++sp) x = mfma32(kf[sp], qf[sp], x);
; #pragma unroll
;         for (int i = 0; i < 16; ++i) p[i] = ex2(x[i]);
;     } else {
;         x = qk_tile(kf, qf);
; #pragma unroll
;         for (int g = 0; g < 4; ++g) {
;             const f32x4 fs = *(const LAS f32x4*)(fsp + 16 * (g >> 1) + 8 * h + 4 * (g & 1));
; #pragma unroll
;             for (int e = 0; e < 4; ++e) p[4 * g + e] = ex2(x[4 * g + e] + (fm - fs[e]));
;         }
;     }
;     if (diag) {
; #pragma unroll
;         for (int i = 0; i < 16; ++i) if (kidx(i, h) > r) p[i] = 0.f;
;     }
; template <int MODE>
; DI void attn_wg2_item(const bf16_t* Qm, const bf16_t* Km, const bf16_t* Vtm, const float* Fb, const float* KMPb, const bf16_t* G, bf16_t* Y, int bh, int qb2, int halfq, int mixer, float Mb, LAS unsigned char* lds, int tid, int wave, int lane) {
;     ...
;             if (actA || actB) {
;                 bf16x8 kf[4], vf[2][2];
; #pragma unroll
;                 for (int sp = 0; sp < 4; ++sp) kf[sp] = *(LAS bf16x8*)(lb + kra + kk * 32 * 144 + sp * 32);
; #pragma unroll
;                 for (int dd = 0; dd < 2; ++dd)
; #pragma unroll
;                     for (int s = 0; s < 2; ++s) vf[dd][s] = *(LAS bf16x8*)(lb + vra + dd * 32 * 144 + kk * 64 + s * 32);
;                 float offA = mb2, offB = mb2;
;                 if (MODE == 2) { offA = ((nb == qblkA) || ((selA >> nb) & 1u)) ? mb2 : NEGI; offB = ((nb == qblkB) || ((selB >> nb) & 1u)) ? mb2 : NEGI; }
;                 const LAS float* fsp = (const LAS float*)(lb + AW_F) + kk * 32;
;                 if (actA) sub_tile<MODE>(kf, vf, qfA, oA0, oA1, lA, tau == qtA, offA, fmA, fsp, r, h);
.LBB0_403:
	s_or_b64 exec, exec, s[64:65]
	s_cmp_le_i32 s87, s84
	s_cselect_b64 s[48:49], -1, 0
	s_cmp_le_i32 s87, s85
	s_cselect_b64 s[64:65], -1, 0
	s_and_b64 s[66:67], s[48:49], vcc
	s_and_b64 s[48:49], s[64:65], s[46:47]
	s_or_b64 s[64:65], s[66:67], s[48:49]
	s_and_saveexec_b64 s[46:47], s[64:65]
	s_cbranch_execz .LBB0_413
	s_waitcnt lgkmcnt(7)
	ds_read_b128 v[152:155], v14
	s_waitcnt lgkmcnt(7)
	ds_read_b128 v[148:151], v14 offset:32
	s_waitcnt lgkmcnt(7)
	ds_read_b128 v[144:147], v14 offset:64
	s_waitcnt lgkmcnt(7)
	ds_read_b128 v[140:143], v14 offset:96
	s_waitcnt lgkmcnt(7)
	ds_read_b128 v[136:139], v0 offset:9216
	s_waitcnt lgkmcnt(7)
	ds_read_b128 v[132:135], v0 offset:9248
	s_waitcnt lgkmcnt(7)
	ds_read_b128 v[128:131], v0 offset:13824
	s_waitcnt lgkmcnt(7)
	ds_read_b128 v[10:13], v0 offset:13856
	s_and_saveexec_b64 s[64:65], s[66:67]
	s_cbranch_execz .LBB0_408
	s_cmp_lg_u32 s87, s84
	s_waitcnt lgkmcnt(7)
	v_mfma_f32_32x32x16_bf16 v[80:95], v[152:155], v[96:99], v[208:223]
	s_waitcnt lgkmcnt(6)
	v_mfma_f32_32x32x16_bf16 v[80:95], v[148:151], v[100:103], v[80:95]
	s_waitcnt lgkmcnt(5)
	v_mfma_f32_32x32x16_bf16 v[80:95], v[144:147], v[104:107], v[80:95]
	s_waitcnt lgkmcnt(4)
	v_mfma_f32_32x32x16_bf16 v[80:95], v[140:143], v[108:111], v[80:95]
	s_nop 11
	v_exp_f32_e32 v0, v80
	v_exp_f32_e32 v14, v81
	v_exp_f32_e32 v15, v82
	v_exp_f32_e32 v80, v83
	v_exp_f32_e32 v83, v84
	v_exp_f32_e32 v84, v85
	v_exp_f32_e32 v188, v86
	v_exp_f32_e32 v87, v87
	v_exp_f32_e32 v81, v88
	v_exp_f32_e32 v82, v89
	v_exp_f32_e32 v85, v90
	v_exp_f32_e32 v86, v91
	v_exp_f32_e32 v88, v92
	v_exp_f32_e32 v89, v93
	v_exp_f32_e32 v90, v94
	v_exp_f32_e32 v91, v95
	s_cbranch_scc1 .LBB0_407
	v_cndmask_b32_e64 v92, v0, 0, s[12:13]
	v_cndmask_b32_e64 v0, v92, v0, s[14:15]
	v_cndmask_b32_e64 v92, v81, 0, s[28:29]
	v_cndmask_b32_e64 v14, 0, v14, s[14:15]
	v_cndmask_b32_e64 v15, v15, 0, s[16:17]
	v_cndmask_b32_e64 v80, v80, 0, s[18:19]
	v_cndmask_b32_e64 v83, v83, 0, s[20:21]
	v_cndmask_b32_e64 v84, v84, 0, s[22:23]
	v_cndmask_b32_e64 v188, v188, 0, s[24:25]
	v_cndmask_b32_e64 v87, v87, 0, s[26:27]
	v_cndmask_b32_e64 v81, v92, v81, s[30:31]
	v_cndmask_b32_e64 v82, 0, v82, s[30:31]
	v_cndmask_b32_e64 v85, v85, 0, s[34:35]
	v_cndmask_b32_e64 v86, v86, 0, s[36:37]
	v_cndmask_b32_e64 v88, v88, 0, s[38:39]
	v_cndmask_b32_e64 v89, v89, 0, s[40:41]
	v_cndmask_b32_e64 v90, v90, 0, s[42:43]
	v_cndmask_b32_e64 v91, v91, 0, s[44:45]

; #define LAS __attribute__((address_space(3)))
; DI f32x16 mfma32(bf16x8 a, bf16x8 b, f32x16 c) { return __builtin_amdgcn_mfma_f32_32x32x16_bf16(a, b, c, 0, 0, 0); }
; DI float ex2(float x) { return __builtin_amdgcn_exp2f(x); }
; template <int MODE>
; DI void sub_tile(const bf16x8 (&kf)[4], const bf16x8 (&vf)[2][2], const bf16x8 (&qf)[4], f32x16& o0, f32x16& o1, float& l, bool diag, float offs, float fm, const LAS float* fsp, int r, int h) {
;     ...
;     if (MODE == 2) {
; #pragma unroll
;         for (int i = 0; i < 16; ++i) x[i] = offs;
; #pragma unroll
;         for (int sp = 0; sp < 4; ++sp) x = mfma32(kf[sp], qf[sp], x);
; #pragma unroll
;         for (int i = 0; i < 16; ++i) p[i] = ex2(x[i]);
;     } else {
;         x = qk_tile(kf, qf);
; #pragma unroll
;         for (int g = 0; g < 4; ++g) {
;             const f32x4 fs = *(const LAS f32x4*)(fsp + 16 * (g >> 1) + 8 * h + 4 * (g & 1));
; #pragma unroll
;             for (int e = 0; e < 4; ++e) p[4 * g + e] = ex2(x[4 * g + e] + (fm - fs[e]));
;         }
;     }
;     if (diag) {
; #pragma unroll
;         for (int i = 0; i < 16; ++i) if (kidx(i, h) > r) p[i] = 0.f;
;     }
; template <int MODE>
; DI void attn_wg2_item(const bf16_t* Qm, const bf16_t* Km, const bf16_t* Vtm, const float* Fb, const float* KMPb, const bf16_t* G, bf16_t* Y, int bh, int qb2, int halfq, int mixer, float Mb, LAS unsigned char* lds, int tid, int wave, int lane) {
;     ...
;                 if (MODE == 2) { offA = ((nb == qblkA) || ((selA >> nb) & 1u)) ? mb2 : NEGI; offB = ((nb == qblkB) || ((selB >> nb) & 1u)) ? mb2 : NEGI; }
;                 const LAS float* fsp = (const LAS float*)(lb + AW_F) + kk * 32;
;                 if (actA) sub_tile<MODE>(kf, vf, qfA, oA0, oA1, lA, tau == qtA, offA, fmA, fsp, r, h);
;                 if (actB) sub_tile<MODE>(kf, vf, qfB, oB0, oB1, lB, tau == qtB, offB, fmB, fsp, r, h);
.LBB0_408:
	s_or_b64 exec, exec, s[64:65]
	s_and_saveexec_b64 s[64:65], s[48:49]
	s_cbranch_execz .LBB0_412
	s_cmp_lg_u32 s87, s85
	s_waitcnt lgkmcnt(7)
	v_mfma_f32_32x32x16_bf16 v[80:95], v[152:155], v[112:115], v[224:239]
	s_waitcnt lgkmcnt(6)
	v_mfma_f32_32x32x16_bf16 v[80:95], v[148:151], v[116:119], v[80:95]
	s_waitcnt lgkmcnt(5)
	v_mfma_f32_32x32x16_bf16 v[80:95], v[144:147], v[120:123], v[80:95]
	s_waitcnt lgkmcnt(4)
	v_mfma_f32_32x32x16_bf16 v[80:95], v[140:143], v[124:127], v[80:95]
	s_nop 11
	v_exp_f32_e32 v142, v80
	v_exp_f32_e32 v143, v81
	v_exp_f32_e32 v140, v82
	v_exp_f32_e32 v141, v83
	v_exp_f32_e32 v84, v84
	v_exp_f32_e32 v85, v85
	v_exp_f32_e32 v86, v86
	v_exp_f32_e32 v87, v87
	v_exp_f32_e32 v88, v88
	v_exp_f32_e32 v0, v89
	v_exp_f32_e32 v14, v90
	v_exp_f32_e32 v15, v91
	v_exp_f32_e32 v80, v92
	v_exp_f32_e32 v81, v93
	v_exp_f32_e32 v82, v94
	v_exp_f32_e32 v83, v95
	s_cbranch_scc1 .LBB0_411
	v_cndmask_b32_e64 v89, v142, 0, s[12:13]
	v_cndmask_b32_e64 v142, v89, v142, s[14:15]
	v_cndmask_b32_e64 v89, v88, 0, s[28:29]
	v_cndmask_b32_e64 v143, 0, v143, s[14:15]
	v_cndmask_b32_e64 v140, v140, 0, s[16:17]
	v_cndmask_b32_e64 v141, v141, 0, s[18:19]
	v_cndmask_b32_e64 v84, v84, 0, s[20:21]
	v_cndmask_b32_e64 v85, v85, 0, s[22:23]
	v_cndmask_b32_e64 v86, v86, 0, s[24:25]
	v_cndmask_b32_e64 v87, v87, 0, s[26:27]
	v_cndmask_b32_e64 v88, v89, v88, s[30:31]
	v_cndmask_b32_e64 v0, 0, v0, s[30:31]
	v_cndmask_b32_e64 v14, v14, 0, s[34:35]
	v_cndmask_b32_e64 v15, v15, 0, s[36:37]
	v_cndmask_b32_e64 v80, v80, 0, s[38:39]
	v_cndmask_b32_e64 v81, v81, 0, s[40:41]
	v_cndmask_b32_e64 v82, v82, 0, s[42:43]
	v_cndmask_b32_e64 v83, v83, 0, s[44:45]
